# GEMM main loop re-sequenced: 2 merged phases per K-step (32 MFMA between barriers, LDS reads complete before the barrier, saddr stage loads)
# speedup vs baseline: 1.0180x; 1.0180x over previous
.LBB0_512:
	s_and_b32 s23, s11, 3
	s_lshr_b32 s76, s14, 6
	s_lshl_b32 s11, s10, 13
	s_lshl_b32 s20, s23, 5
	s_lshl_b32 s15, s23, 12
	s_and_b64 s[6:7], exec, s[6:7]
	s_cselect_b32 s77, s59, s58
	s_add_i32 m0, s81, 0x18000
	v_lshl_add_u64 v[10:11], v[10:11], 0, s[52:53]
	s_waitcnt vmcnt(2)
	s_barrier
	global_load_lds_dwordx4 v[10:11], off
	v_lshl_add_u64 v[8:9], v[8:9], 0, s[52:53]
	s_add_i32 m0, s81, 0x1a000
	s_add_i32 s68, s81, 0x8000
	global_load_lds_dwordx4 v[8:9], off
	v_lshl_add_u64 v[6:7], v[6:7], 0, s[52:53]
	s_mov_b32 m0, s68
	s_add_i32 s14, s81, 0xa000
	global_load_lds_dwordx4 v[6:7], off
	v_lshl_add_u64 v[4:5], v[4:5], 0, s[52:53]
	s_mov_b32 m0, s14
	v_lshl_add_u64 v[2:3], v[2:3], 0, s[52:53]
	global_load_lds_dwordx4 v[4:5], off
	s_add_i32 m0, s81, 0x1c000
	v_lshl_add_u64 v[0:1], v[0:1], 0, s[52:53]
	global_load_lds_dwordx4 v[2:3], off
	s_add_i32 m0, s81, 0x1e000
	v_lshlrev_b32_e32 v2, 2, v12
	global_load_lds_dwordx4 v[0:1], off
	v_bfe_u32 v0, v12, 4, 2
	v_and_b32_e32 v1, 15, v12
	v_lshlrev_b32_e32 v148, 4, v0
	s_lshl_b32 s37, s2, 3
	v_lshl_or_b32 v151, s10, 6, v1
	v_lshl_or_b32 v1, v1, 6, v148
	v_and_b32_e32 v2, 32, v2
	s_abs_i32 s64, s37
	v_bitop3_b32 v3, v1, s11, v2 bitop3:0xde
	v_bitop3_b32 v185, s15, v1, v2 bitop3:0xf6
	v_cvt_f32_u32_e32 v1, s64
	v_lshl_add_u64 v[156:157], s[8:9], 0, v[148:149]
	v_cmp_eq_u32_e64 s[6:7], 0, v0
	v_lshl_or_b32 v186, v0, 3, s20
	v_rcp_iflag_f32_e32 v1, v1
	v_lshl_or_b32 v187, v0, 2, s20
	s_sub_i32 s8, 0, s64
	v_add_u32_e32 v0, v18, v16
	v_mul_f32_e32 v1, 0x4f7ffffe, v1
	v_cvt_u32_f32_e32 v1, v1
	s_waitcnt vmcnt(6)
	v_add_lshl_u32 v148, v0, v17, 1
	v_add_u32_e32 v0, v15, v13
	v_readfirstlane_b32 s9, v1
	s_mul_i32 s8, s8, s9
	s_mul_hi_u32 s8, s9, s8
	v_lshl_add_u64 v[158:159], s[26:27], 0, v[148:149]
	v_add_lshl_u32 v148, v0, v14, 1
	s_add_i32 s15, s76, -2
	s_mov_b32 s83, s82
	s_mov_b32 s90, s82
	s_mov_b32 s91, s82
	s_mov_b32 s36, 0
	s_ashr_i32 s46, s77, 31
	s_ashr_i32 s73, s34, 31
	s_mov_b32 s43, s27
	s_lshr_b32 s97, s42, 3
	s_bfe_i32 s2, s2, 0x1001c
	s_add_i32 s24, s9, s8
	v_lshl_add_u64 v[160:161], s[26:27], 0, v[148:149]
	v_add_u32_e32 v188, 0, v3
	s_barrier
	s_branch .LBB0_515

.LBB0_522:
	s_add_i32 s72, s78, 2
	s_add_u32 s79, s10, 0x80
	s_addc_u32 vcc_lo, s11, 0
	v_add_u32_e32 v148, 0x10000, v185
	s_cmp_eq_u32 s15, s78
	s_cselect_b32 s78, s12, s84
	s_cselect_b32 vcc_hi, s49, vcc_lo
	s_cselect_b32 vcc_lo, s48, s79
	s_cselect_b32 s79, s13, s85
	ds_read_b128 v[128:131], v148 offset:0
	ds_read_b128 v[132:135], v148 offset:1024
	ds_read_b128 v[136:139], v148 offset:2048
	ds_read_b128 v[140:143], v148 offset:3072
	ds_read_b128 v[218:221], v148 offset:16384
	ds_read_b128 v[222:225], v148 offset:17408
	ds_read_b128 v[226:229], v148 offset:18432
	ds_read_b128 v[230:233], v148 offset:19456
	ds_read_b128 v[162:165], v188 offset:0
	ds_read_b128 v[190:193], v188 offset:1024
	ds_read_b128 v[194:197], v188 offset:2048
	ds_read_b128 v[198:201], v188 offset:3072
	ds_read_b128 v[202:205], v188 offset:4096
	ds_read_b128 v[206:209], v188 offset:5120
	ds_read_b128 v[210:213], v188 offset:6144
	ds_read_b128 v[214:217], v188 offset:7168
	s_add_u32 s4, s10, s26
	s_addc_u32 s5, s11, 0
	s_add_i32 m0, s81, 0xc000
	s_nop 0
	global_load_lds_dwordx4 v152, s[4:5]
	s_add_i32 m0, s81, 0xe000
	s_nop 0
	global_load_lds_dwordx4 v144, s[4:5]
	s_waitcnt vmcnt(8)
	s_waitcnt lgkmcnt(0)
	s_barrier
	s_setprio 1
	v_mfma_f32_16x16x32_bf16 v[124:127], v[128:131], v[162:165], v[124:127]
	v_mfma_f32_16x16x32_bf16 v[116:119], v[136:139], v[162:165], v[116:119]
	v_mfma_f32_16x16x32_bf16 v[120:123], v[128:131], v[194:197], v[120:123]
	v_mfma_f32_16x16x32_bf16 v[112:115], v[136:139], v[194:197], v[112:115]
	v_mfma_f32_16x16x32_bf16 v[92:95], v[128:131], v[202:205], v[92:95]
	v_mfma_f32_16x16x32_bf16 v[84:87], v[136:139], v[202:205], v[84:87]
	v_mfma_f32_16x16x32_bf16 v[88:91], v[128:131], v[210:213], v[88:91]
	v_mfma_f32_16x16x32_bf16 v[80:83], v[136:139], v[210:213], v[80:83]
	v_mfma_f32_16x16x32_bf16 v[124:127], v[132:135], v[190:193], v[124:127]
	v_mfma_f32_16x16x32_bf16 v[116:119], v[140:143], v[190:193], v[116:119]
	v_mfma_f32_16x16x32_bf16 v[120:123], v[132:135], v[198:201], v[120:123]
	v_mfma_f32_16x16x32_bf16 v[112:115], v[140:143], v[198:201], v[112:115]
	v_mfma_f32_16x16x32_bf16 v[92:95], v[132:135], v[206:209], v[92:95]
	v_mfma_f32_16x16x32_bf16 v[84:87], v[140:143], v[206:209], v[84:87]
	v_mfma_f32_16x16x32_bf16 v[88:91], v[132:135], v[214:217], v[88:91]
	v_mfma_f32_16x16x32_bf16 v[80:83], v[140:143], v[214:217], v[80:83]
	v_mfma_f32_16x16x32_bf16 v[108:111], v[218:221], v[162:165], v[108:111]
	v_mfma_f32_16x16x32_bf16 v[100:103], v[226:229], v[162:165], v[100:103]
	v_mfma_f32_16x16x32_bf16 v[104:107], v[218:221], v[194:197], v[104:107]
	v_mfma_f32_16x16x32_bf16 v[96:99], v[226:229], v[194:197], v[96:99]
	v_mfma_f32_16x16x32_bf16 v[76:79], v[218:221], v[202:205], v[76:79]
	v_mfma_f32_16x16x32_bf16 v[68:71], v[226:229], v[202:205], v[68:71]
	v_mfma_f32_16x16x32_bf16 v[72:75], v[218:221], v[210:213], v[72:75]
	v_mfma_f32_16x16x32_bf16 v[64:67], v[226:229], v[210:213], v[64:67]
	v_mfma_f32_16x16x32_bf16 v[108:111], v[222:225], v[190:193], v[108:111]
	v_mfma_f32_16x16x32_bf16 v[100:103], v[230:233], v[190:193], v[100:103]
	v_mfma_f32_16x16x32_bf16 v[104:107], v[222:225], v[198:201], v[104:107]
	v_mfma_f32_16x16x32_bf16 v[96:99], v[230:233], v[198:201], v[96:99]
	v_mfma_f32_16x16x32_bf16 v[76:79], v[222:225], v[206:209], v[76:79]
	v_mfma_f32_16x16x32_bf16 v[68:71], v[230:233], v[206:209], v[68:71]
	v_mfma_f32_16x16x32_bf16 v[72:75], v[222:225], v[214:217], v[72:75]
	v_mfma_f32_16x16x32_bf16 v[64:67], v[230:233], v[214:217], v[64:67]
	s_setprio 0
	s_barrier
	ds_read_b128 v[162:165], v188 offset:16384
	ds_read_b128 v[190:193], v188 offset:17408
	ds_read_b128 v[194:197], v188 offset:18432
	ds_read_b128 v[198:201], v188 offset:19456
	ds_read_b128 v[202:205], v188 offset:20480
	ds_read_b128 v[206:209], v188 offset:21504
	ds_read_b128 v[210:213], v188 offset:22528
	ds_read_b128 v[214:217], v188 offset:23552
	s_add_i32 m0, s81, 0x10000
	s_nop 0
	global_load_lds_dwordx4 v154, s[78:79]
	s_add_i32 m0, s81, 0x12000
	s_nop 0
	global_load_lds_dwordx4 v146, s[78:79]
	s_add_i32 m0, s81, 0x0
	s_nop 0
	global_load_lds_dwordx4 v152, vcc
	s_add_i32 m0, s81, 0x2000
	s_nop 0
	global_load_lds_dwordx4 v144, vcc
	s_add_u32 s4, s78, s26
	s_addc_u32 s5, s79, 0
	s_add_i32 m0, s81, 0x14000
	s_nop 0
	global_load_lds_dwordx4 v154, s[4:5]
	s_add_i32 m0, s81, 0x16000
	s_nop 0
	global_load_lds_dwordx4 v146, s[4:5]
	s_waitcnt vmcnt(8)
	s_waitcnt lgkmcnt(0)
	s_barrier
	s_setprio 1
	v_mfma_f32_16x16x32_bf16 v[60:63], v[128:131], v[162:165], v[60:63]
	v_mfma_f32_16x16x32_bf16 v[56:59], v[136:139], v[162:165], v[56:59]
	v_mfma_f32_16x16x32_bf16 v[52:55], v[128:131], v[194:197], v[52:55]
	v_mfma_f32_16x16x32_bf16 v[48:51], v[136:139], v[194:197], v[48:51]
	v_mfma_f32_16x16x32_bf16 v[28:31], v[128:131], v[202:205], v[28:31]
	v_mfma_f32_16x16x32_bf16 v[20:23], v[136:139], v[202:205], v[20:23]
	v_mfma_f32_16x16x32_bf16 v[24:27], v[128:131], v[210:213], v[24:27]
	v_mfma_f32_16x16x32_bf16 v[16:19], v[136:139], v[210:213], v[16:19]
	v_mfma_f32_16x16x32_bf16 v[60:63], v[132:135], v[190:193], v[60:63]
	v_mfma_f32_16x16x32_bf16 v[56:59], v[140:143], v[190:193], v[56:59]
	v_mfma_f32_16x16x32_bf16 v[52:55], v[132:135], v[198:201], v[52:55]
	v_mfma_f32_16x16x32_bf16 v[48:51], v[140:143], v[198:201], v[48:51]
	v_mfma_f32_16x16x32_bf16 v[28:31], v[132:135], v[206:209], v[28:31]
	v_mfma_f32_16x16x32_bf16 v[20:23], v[140:143], v[206:209], v[20:23]
	v_mfma_f32_16x16x32_bf16 v[24:27], v[132:135], v[214:217], v[24:27]
	v_mfma_f32_16x16x32_bf16 v[16:19], v[140:143], v[214:217], v[16:19]
	v_mfma_f32_16x16x32_bf16 v[44:47], v[218:221], v[162:165], v[44:47]
	v_mfma_f32_16x16x32_bf16 v[36:39], v[226:229], v[162:165], v[36:39]
	v_mfma_f32_16x16x32_bf16 v[40:43], v[218:221], v[194:197], v[40:43]
	v_mfma_f32_16x16x32_bf16 v[32:35], v[226:229], v[194:197], v[32:35]
	v_mfma_f32_16x16x32_bf16 v[12:15], v[218:221], v[202:205], v[12:15]
	v_mfma_f32_16x16x32_bf16 v[4:7], v[226:229], v[202:205], v[4:7]
	v_mfma_f32_16x16x32_bf16 v[8:11], v[218:221], v[210:213], v[8:11]
	v_mfma_f32_16x16x32_bf16 v[0:3], v[226:229], v[210:213], v[0:3]
	v_mfma_f32_16x16x32_bf16 v[44:47], v[222:225], v[190:193], v[44:47]
	v_mfma_f32_16x16x32_bf16 v[36:39], v[230:233], v[190:193], v[36:39]
	v_mfma_f32_16x16x32_bf16 v[40:43], v[222:225], v[198:201], v[40:43]
	v_mfma_f32_16x16x32_bf16 v[32:35], v[230:233], v[198:201], v[32:35]
	v_mfma_f32_16x16x32_bf16 v[12:15], v[222:225], v[206:209], v[12:15]
	v_mfma_f32_16x16x32_bf16 v[4:7], v[230:233], v[206:209], v[4:7]
	v_mfma_f32_16x16x32_bf16 v[8:11], v[222:225], v[214:217], v[8:11]
	v_mfma_f32_16x16x32_bf16 v[0:3], v[230:233], v[214:217], v[0:3]
	s_setprio 0
	s_barrier
	ds_read_b128 v[128:131], v148 offset:32768
	ds_read_b128 v[132:135], v148 offset:33792
	ds_read_b128 v[136:139], v148 offset:34816
	ds_read_b128 v[140:143], v148 offset:35840
	ds_read_b128 v[218:221], v148 offset:49152
	ds_read_b128 v[222:225], v148 offset:50176
	ds_read_b128 v[226:229], v148 offset:51200
	ds_read_b128 v[230:233], v148 offset:52224
	ds_read_b128 v[162:165], v188 offset:32768
	ds_read_b128 v[190:193], v188 offset:33792
	ds_read_b128 v[194:197], v188 offset:34816
	ds_read_b128 v[198:201], v188 offset:35840
	ds_read_b128 v[202:205], v188 offset:36864
	ds_read_b128 v[206:209], v188 offset:37888
	ds_read_b128 v[210:213], v188 offset:38912
	ds_read_b128 v[214:217], v188 offset:39936
	s_add_u32 s4, vcc_lo, s26
	s_addc_u32 s5, vcc_hi, 0
	s_add_i32 m0, s81, 0x4000
	s_nop 0
	global_load_lds_dwordx4 v152, s[4:5]
	s_add_i32 m0, s81, 0x6000
	s_nop 0
	global_load_lds_dwordx4 v144, s[4:5]
	s_waitcnt vmcnt(8)
	s_waitcnt lgkmcnt(0)
	s_barrier
	s_setprio 1
	v_mfma_f32_16x16x32_bf16 v[124:127], v[128:131], v[162:165], v[124:127]
	v_mfma_f32_16x16x32_bf16 v[116:119], v[136:139], v[162:165], v[116:119]
	v_mfma_f32_16x16x32_bf16 v[120:123], v[128:131], v[194:197], v[120:123]
	v_mfma_f32_16x16x32_bf16 v[112:115], v[136:139], v[194:197], v[112:115]
	v_mfma_f32_16x16x32_bf16 v[92:95], v[128:131], v[202:205], v[92:95]
	v_mfma_f32_16x16x32_bf16 v[84:87], v[136:139], v[202:205], v[84:87]
	v_mfma_f32_16x16x32_bf16 v[88:91], v[128:131], v[210:213], v[88:91]
	v_mfma_f32_16x16x32_bf16 v[80:83], v[136:139], v[210:213], v[80:83]
	v_mfma_f32_16x16x32_bf16 v[124:127], v[132:135], v[190:193], v[124:127]
	v_mfma_f32_16x16x32_bf16 v[116:119], v[140:143], v[190:193], v[116:119]
	v_mfma_f32_16x16x32_bf16 v[120:123], v[132:135], v[198:201], v[120:123]
	v_mfma_f32_16x16x32_bf16 v[112:115], v[140:143], v[198:201], v[112:115]
	v_mfma_f32_16x16x32_bf16 v[92:95], v[132:135], v[206:209], v[92:95]
	v_mfma_f32_16x16x32_bf16 v[84:87], v[140:143], v[206:209], v[84:87]
	v_mfma_f32_16x16x32_bf16 v[88:91], v[132:135], v[214:217], v[88:91]
	v_mfma_f32_16x16x32_bf16 v[80:83], v[140:143], v[214:217], v[80:83]
	v_mfma_f32_16x16x32_bf16 v[108:111], v[218:221], v[162:165], v[108:111]
	v_mfma_f32_16x16x32_bf16 v[100:103], v[226:229], v[162:165], v[100:103]
	v_mfma_f32_16x16x32_bf16 v[104:107], v[218:221], v[194:197], v[104:107]
	v_mfma_f32_16x16x32_bf16 v[96:99], v[226:229], v[194:197], v[96:99]
	v_mfma_f32_16x16x32_bf16 v[76:79], v[218:221], v[202:205], v[76:79]
	v_mfma_f32_16x16x32_bf16 v[68:71], v[226:229], v[202:205], v[68:71]
	v_mfma_f32_16x16x32_bf16 v[72:75], v[218:221], v[210:213], v[72:75]
	v_mfma_f32_16x16x32_bf16 v[64:67], v[226:229], v[210:213], v[64:67]
	v_mfma_f32_16x16x32_bf16 v[108:111], v[222:225], v[190:193], v[108:111]
	v_mfma_f32_16x16x32_bf16 v[100:103], v[230:233], v[190:193], v[100:103]
	v_mfma_f32_16x16x32_bf16 v[104:107], v[222:225], v[198:201], v[104:107]
	v_mfma_f32_16x16x32_bf16 v[96:99], v[230:233], v[198:201], v[96:99]
	v_mfma_f32_16x16x32_bf16 v[76:79], v[222:225], v[206:209], v[76:79]
	v_mfma_f32_16x16x32_bf16 v[68:71], v[230:233], v[206:209], v[68:71]
	v_mfma_f32_16x16x32_bf16 v[72:75], v[222:225], v[214:217], v[72:75]
	v_mfma_f32_16x16x32_bf16 v[64:67], v[230:233], v[214:217], v[64:67]
	s_setprio 0
	s_barrier
	ds_read_b128 v[162:165], v188 offset:49152
	ds_read_b128 v[190:193], v188 offset:50176
	ds_read_b128 v[194:197], v188 offset:51200
	ds_read_b128 v[198:201], v188 offset:52224
	ds_read_b128 v[202:205], v188 offset:53248
	ds_read_b128 v[206:209], v188 offset:54272
	ds_read_b128 v[210:213], v188 offset:55296
	ds_read_b128 v[214:217], v188 offset:56320
	s_add_u32 s4, s78, 0x80
	s_addc_u32 s5, s79, 0
	s_add_i32 m0, s81, 0x18000
	s_nop 0
	global_load_lds_dwordx4 v154, s[4:5]
	s_add_i32 m0, s81, 0x1a000
	s_nop 0
	global_load_lds_dwordx4 v146, s[4:5]
	s_add_u32 s4, vcc_lo, 0x80
	s_addc_u32 s5, vcc_hi, 0
	s_add_i32 m0, s81, 0x8000
	s_nop 0
	global_load_lds_dwordx4 v152, s[4:5]
	s_add_i32 m0, s81, 0xa000
	s_nop 0
	global_load_lds_dwordx4 v144, s[4:5]
	s_add_u32 s4, s78, s26
	s_addc_u32 s5, s79, 0
	s_add_u32 s4, s4, 0x80
	s_addc_u32 s5, s5, 0
	s_add_i32 m0, s81, 0x1c000
	s_nop 0
	global_load_lds_dwordx4 v154, s[4:5]
	s_add_i32 m0, s81, 0x1e000
	s_nop 0
	global_load_lds_dwordx4 v146, s[4:5]
	s_waitcnt vmcnt(8)
	s_waitcnt lgkmcnt(0)
	s_barrier
	s_setprio 1
	v_mfma_f32_16x16x32_bf16 v[60:63], v[128:131], v[162:165], v[60:63]
	v_mfma_f32_16x16x32_bf16 v[56:59], v[136:139], v[162:165], v[56:59]
	v_mfma_f32_16x16x32_bf16 v[52:55], v[128:131], v[194:197], v[52:55]
	v_mfma_f32_16x16x32_bf16 v[48:51], v[136:139], v[194:197], v[48:51]
	v_mfma_f32_16x16x32_bf16 v[28:31], v[128:131], v[202:205], v[28:31]
	v_mfma_f32_16x16x32_bf16 v[20:23], v[136:139], v[202:205], v[20:23]
	v_mfma_f32_16x16x32_bf16 v[24:27], v[128:131], v[210:213], v[24:27]
	v_mfma_f32_16x16x32_bf16 v[16:19], v[136:139], v[210:213], v[16:19]
	v_mfma_f32_16x16x32_bf16 v[60:63], v[132:135], v[190:193], v[60:63]
	v_mfma_f32_16x16x32_bf16 v[56:59], v[140:143], v[190:193], v[56:59]
	v_mfma_f32_16x16x32_bf16 v[52:55], v[132:135], v[198:201], v[52:55]
	v_mfma_f32_16x16x32_bf16 v[48:51], v[140:143], v[198:201], v[48:51]
	v_mfma_f32_16x16x32_bf16 v[28:31], v[132:135], v[206:209], v[28:31]
	v_mfma_f32_16x16x32_bf16 v[20:23], v[140:143], v[206:209], v[20:23]
	v_mfma_f32_16x16x32_bf16 v[24:27], v[132:135], v[214:217], v[24:27]
	v_mfma_f32_16x16x32_bf16 v[16:19], v[140:143], v[214:217], v[16:19]
	v_mfma_f32_16x16x32_bf16 v[44:47], v[218:221], v[162:165], v[44:47]
	v_mfma_f32_16x16x32_bf16 v[36:39], v[226:229], v[162:165], v[36:39]
	v_mfma_f32_16x16x32_bf16 v[40:43], v[218:221], v[194:197], v[40:43]
	v_mfma_f32_16x16x32_bf16 v[32:35], v[226:229], v[194:197], v[32:35]
	v_mfma_f32_16x16x32_bf16 v[12:15], v[218:221], v[202:205], v[12:15]
	v_mfma_f32_16x16x32_bf16 v[4:7], v[226:229], v[202:205], v[4:7]
	v_mfma_f32_16x16x32_bf16 v[8:11], v[218:221], v[210:213], v[8:11]
	v_mfma_f32_16x16x32_bf16 v[0:3], v[226:229], v[210:213], v[0:3]
	v_mfma_f32_16x16x32_bf16 v[44:47], v[222:225], v[190:193], v[44:47]
	v_mfma_f32_16x16x32_bf16 v[36:39], v[230:233], v[190:193], v[36:39]
	v_mfma_f32_16x16x32_bf16 v[40:43], v[222:225], v[198:201], v[40:43]
	v_mfma_f32_16x16x32_bf16 v[32:35], v[230:233], v[198:201], v[32:35]
	v_mfma_f32_16x16x32_bf16 v[12:15], v[222:225], v[206:209], v[12:15]
	v_mfma_f32_16x16x32_bf16 v[4:7], v[230:233], v[206:209], v[4:7]
	v_mfma_f32_16x16x32_bf16 v[8:11], v[222:225], v[214:217], v[8:11]
	v_mfma_f32_16x16x32_bf16 v[0:3], v[230:233], v[214:217], v[0:3]
	s_setprio 0
	s_add_u32 s10, s10, 0x100
	s_addc_u32 s11, s11, 0
	s_add_u32 s84, s84, 0x100
	s_addc_u32 s85, s85, 0
	s_cmp_ge_u32 s72, s76
	s_mov_b32 s78, s72
	s_barrier
	s_cbranch_scc0 .LBB0_522
	v_lshl_add_u32 v162, s20, 8, v151
	s_cmp_lt_i32 s45, 2
	s_mov_b64 s[10:11], -1
	s_cbranch_scc1 .LBB0_537
	s_cmp_gt_i32 s45, 2
	s_cbranch_scc0 .LBB0_534
	s_add_i32 s10, s25, 2
	s_cmp_gt_u32 s10, 4
	s_mov_b64 s[10:11], -1
	s_cbranch_scc0 .LBB0_531
	s_add_i32 s10, s25, -3
	s_cmp_gt_u32 s10, 2
	v_lshl_or_b32 v148, s25, 8, v186
	s_mov_b64 s[10:11], -1
	s_cbranch_scc0 .LBB0_528
	v_ashrrev_i32_e32 v128, 31, v162
	v_mul_lo_u32 v134, s29, v162
	v_mul_lo_u32 v136, s28, v128
	v_mad_u64_u32 v[128:129], s[10:11], s28, v162, 0
	v_add3_u32 v129, v129, v136, v134
	v_lshl_add_u64 v[134:135], v[128:129], 1, s[70:71]
	v_ashrrev_i32_e32 v129, 31, v148
	v_mov_b32_e32 v128, v148
	v_lshlrev_b64 v[128:129], 1, v[128:129]
	v_cvt_pk_bf16_f32 v130, v124, v125
	v_cvt_pk_bf16_f32 v131, v126, v127
	v_cvt_pk_bf16_f32 v132, v116, v117
	v_cvt_pk_bf16_f32 v133, v118, v119
	v_lshl_add_u64 v[134:135], v[134:135], 0, v[128:129]
	global_store_dwordx4 v[134:135], v[130:133], off
	s_nop 1
	v_cvt_pk_bf16_f32 v130, v108, v109
	v_cvt_pk_bf16_f32 v131, v110, v111
	v_cvt_pk_bf16_f32 v132, v100, v101
	v_cvt_pk_bf16_f32 v133, v102, v103
	global_store_dwordx4 v[134:135], v[130:133], off offset:256
	v_or_b32_e32 v134, 16, v162
	v_mul_lo_u32 v137, s29, v134
	v_mad_u64_u32 v[134:135], s[10:11], s28, v134, 0
	v_add3_u32 v135, v135, v136, v137
	v_lshl_add_u64 v[134:135], v[134:135], 1, s[70:71]
	v_cvt_pk_bf16_f32 v130, v120, v121
	v_cvt_pk_bf16_f32 v131, v122, v123
	v_cvt_pk_bf16_f32 v132, v112, v113
	v_cvt_pk_bf16_f32 v133, v114, v115
	v_lshl_add_u64 v[134:135], v[134:135], 0, v[128:129]
	global_store_dwordx4 v[134:135], v[130:133], off
	s_nop 1
	v_cvt_pk_bf16_f32 v130, v104, v105
	v_cvt_pk_bf16_f32 v131, v106, v107
	v_cvt_pk_bf16_f32 v132, v96, v97
	v_cvt_pk_bf16_f32 v133, v98, v99
	global_store_dwordx4 v[134:135], v[130:133], off offset:256
	v_or_b32_e32 v134, 32, v162
	v_mul_lo_u32 v137, s29, v134
	v_mad_u64_u32 v[134:135], s[10:11], s28, v134, 0
	v_add3_u32 v135, v135, v136, v137
	v_lshl_add_u64 v[134:135], v[134:135], 1, s[70:71]
	v_cvt_pk_bf16_f32 v130, v92, v93
	v_cvt_pk_bf16_f32 v131, v94, v95
	v_cvt_pk_bf16_f32 v132, v84, v85
	v_cvt_pk_bf16_f32 v133, v86, v87
	v_lshl_add_u64 v[134:135], v[134:135], 0, v[128:129]
	global_store_dwordx4 v[134:135], v[130:133], off
	s_nop 1
	v_cvt_pk_bf16_f32 v130, v76, v77
	v_cvt_pk_bf16_f32 v131, v78, v79
	v_cvt_pk_bf16_f32 v132, v68, v69
	v_cvt_pk_bf16_f32 v133, v70, v71
	global_store_dwordx4 v[134:135], v[130:133], off offset:256
	v_or_b32_e32 v134, 48, v162
	v_mul_lo_u32 v137, s29, v134
	v_mad_u64_u32 v[134:135], s[10:11], s28, v134, 0
	v_add3_u32 v135, v135, v136, v137
	v_lshl_add_u64 v[134:135], v[134:135], 1, s[70:71]
	v_cvt_pk_bf16_f32 v130, v88, v89
	v_cvt_pk_bf16_f32 v131, v90, v91
	v_cvt_pk_bf16_f32 v132, v80, v81
	v_cvt_pk_bf16_f32 v133, v82, v83
	v_lshl_add_u64 v[134:135], v[134:135], 0, v[128:129]
	global_store_dwordx4 v[134:135], v[130:133], off
	s_nop 1
	v_cvt_pk_bf16_f32 v130, v72, v73
	v_cvt_pk_bf16_f32 v131, v74, v75
	v_cvt_pk_bf16_f32 v132, v64, v65
	v_cvt_pk_bf16_f32 v133, v66, v67
	global_store_dwordx4 v[134:135], v[130:133], off offset:256
	v_add_u32_e32 v134, 0x80, v162
	v_ashrrev_i32_e32 v135, 31, v134
	v_mul_lo_u32 v136, s28, v135
	v_mul_lo_u32 v137, s29, v134
	v_mad_u64_u32 v[134:135], s[10:11], s28, v134, 0
	v_add3_u32 v135, v135, v136, v137
	v_lshl_add_u64 v[134:135], v[134:135], 1, s[70:71]
	v_cvt_pk_bf16_f32 v130, v60, v61
	v_cvt_pk_bf16_f32 v131, v62, v63
	v_cvt_pk_bf16_f32 v132, v56, v57
	v_cvt_pk_bf16_f32 v133, v58, v59
	v_lshl_add_u64 v[134:135], v[134:135], 0, v[128:129]
	global_store_dwordx4 v[134:135], v[130:133], off
	s_nop 1
	v_cvt_pk_bf16_f32 v130, v44, v45
	v_cvt_pk_bf16_f32 v131, v46, v47
	v_cvt_pk_bf16_f32 v132, v36, v37
	v_cvt_pk_bf16_f32 v133, v38, v39
	global_store_dwordx4 v[134:135], v[130:133], off offset:256
	v_add_u32_e32 v134, 0x90, v162
	v_ashrrev_i32_e32 v135, 31, v134
	v_mul_lo_u32 v136, s28, v135
	v_mul_lo_u32 v137, s29, v134
	v_mad_u64_u32 v[134:135], s[10:11], s28, v134, 0
	v_add3_u32 v135, v135, v136, v137
	v_lshl_add_u64 v[134:135], v[134:135], 1, s[70:71]
	v_cvt_pk_bf16_f32 v130, v52, v53
	v_cvt_pk_bf16_f32 v131, v54, v55
	v_cvt_pk_bf16_f32 v132, v48, v49
	v_cvt_pk_bf16_f32 v133, v50, v51
	v_lshl_add_u64 v[134:135], v[134:135], 0, v[128:129]
	global_store_dwordx4 v[134:135], v[130:133], off
	s_nop 1
	v_cvt_pk_bf16_f32 v130, v40, v41
	v_cvt_pk_bf16_f32 v131, v42, v43
	v_cvt_pk_bf16_f32 v132, v32, v33
	v_cvt_pk_bf16_f32 v133, v34, v35
	global_store_dwordx4 v[134:135], v[130:133], off offset:256
	v_add_u32_e32 v134, 0xa0, v162
	v_ashrrev_i32_e32 v135, 31, v134
	v_mul_lo_u32 v136, s28, v135
	v_mul_lo_u32 v137, s29, v134
	v_mad_u64_u32 v[134:135], s[10:11], s28, v134, 0
	v_add3_u32 v135, v135, v136, v137
	v_lshl_add_u64 v[134:135], v[134:135], 1, s[70:71]
	v_cvt_pk_bf16_f32 v130, v28, v29
	v_cvt_pk_bf16_f32 v131, v30, v31
	v_cvt_pk_bf16_f32 v132, v20, v21
	v_cvt_pk_bf16_f32 v133, v22, v23
	v_lshl_add_u64 v[134:135], v[134:135], 0, v[128:129]
	global_store_dwordx4 v[134:135], v[130:133], off
	s_nop 1
	v_cvt_pk_bf16_f32 v130, v12, v13
	v_cvt_pk_bf16_f32 v131, v14, v15
	v_cvt_pk_bf16_f32 v132, v4, v5
	v_cvt_pk_bf16_f32 v133, v6, v7
	global_store_dwordx4 v[134:135], v[130:133], off offset:256
	v_add_u32_e32 v134, 0xb0, v162
	v_ashrrev_i32_e32 v135, 31, v134
	v_mul_lo_u32 v136, s28, v135
	v_mul_lo_u32 v137, s29, v134
	v_mad_u64_u32 v[134:135], s[10:11], s28, v134, 0
	v_add3_u32 v135, v135, v136, v137
	v_lshl_add_u64 v[134:135], v[134:135], 1, s[70:71]
	v_cvt_pk_bf16_f32 v130, v24, v25
	v_cvt_pk_bf16_f32 v131, v26, v27
	v_lshl_add_u64 v[134:135], v[134:135], 0, v[128:129]
	v_cvt_pk_bf16_f32 v132, v16, v17
	v_cvt_pk_bf16_f32 v133, v18, v19
	global_store_dwordx4 v[134:135], v[130:133], off
	v_cvt_pk_bf16_f32 v128, v8, v9
	v_cvt_pk_bf16_f32 v129, v10, v11
	s_mov_b64 s[10:11], 0
	s_nop 0
	v_cvt_pk_bf16_f32 v130, v0, v1
	v_cvt_pk_bf16_f32 v131, v2, v3
	global_store_dwordx4 v[134:135], v[128:131], off offset:256
